# grid barrier between LN3 and the next layer's prep_weights removed (no data dependency between those two phases; LN3 outputs are consumed after the prep_weights barrier)
# speedup vs baseline: 1.0068x; 1.0063x over previous
; __global__ void __launch_bounds__(NT, 2) mk_fwd(Params P) {
;     ...
;             } else if (st == 3 || st == 9 || st == 12) {
;                 const float* lg = st == 3 ? P.in[2] : (st == 9 ? P.in[21] : P.in[25]); const float* lb = st == 3 ? P.in[3] : (st == 9 ? P.in[22] : P.in[26]);
;                 ln_pass(P, lg + l * DM, lb + l * DM, l == DEPTH - 1 && st == 12);
;     ...
;             if (l == 0 && st == 0) grid.sync();
;             xcd_barrier(xbar);
.LBB0_789:
	s_or_b64 exec, exec, s[26:27]
	s_mov_b32 s101, 0
	s_cmp_eq_u32 s76, 12
	s_cbranch_scc0 .Lln_noskip
	v_readlane_b32 s80, v255, 14
	s_nop 3
	s_cmp_lt_u32 s80, 3
	s_cbranch_scc0 .Lln_noskip
	s_mov_b32 s101, 0x5a5a5a5a
.Lln_noskip:
	s_mov_b64 s[80:81], 0

; __device__ __forceinline__ void xcd_barrier(const XcdBarrier& b) {
;     asm volatile("s_waitcnt vmcnt(0)" ::: "memory");
;     __syncthreads();
; __global__ void __launch_bounds__(NT, 2) mk_fwd(Params P) {
;     ...
;             if (l == 0 && st == 0) grid.sync();
;             xcd_barrier(xbar);
.LBB0_953:
	s_cmp_eq_u32 s101, 0x5a5a5a5a
	s_cbranch_scc0 .Lxb_do
	s_mov_b32 s101, 0
	s_mov_b64 s[0:1], exec
	s_branch .LBB0_12
